# gemm_in as 256x128 double tiles (two row tiles share one B tile), B double-buffered in LDS, two-pass epilogue
# speedup vs baseline: 1.0678x; 1.0348x over previous
.LBB0_209:
	s_not_b32 s2, s5
	s_add_i32 s2, s8, s2
	s_add_i32 s2, s2, s17
	s_ashr_i32 s3, s2, 31
	s_abs_i32 s2, s2
	s_mul_hi_u32 s5, s2, s72
	s_mul_i32 s8, s5, s4
	s_sub_i32 s2, s2, s8
	s_xor_b32 s3, s3, s16
	s_add_i32 s8, s5, 1
	s_sub_i32 s9, s2, s4
	s_cmp_ge_u32 s2, s4
	s_cselect_b32 s5, s8, s5
	s_cselect_b32 s2, s9, s2
	s_add_i32 s8, s5, 1
	s_cmp_ge_u32 s2, s4
	s_cselect_b32 s2, s8, s5
	s_xor_b32 s2, s2, s3
	s_sub_i32 s2, s2, s3
	s_add_i32 s3, s15, s24
	s_not_b32 s4, s23
	s_add_i32 s4, s4, s3
	s_ashr_i32 s3, s4, 31
	s_abs_i32 s4, s4
	s_mul_i32 s1, s4, s1
	s_mul_hi_u32 s0, s4, s0
	s_add_i32 s0, s0, s1
	s_mul_i32 s1, s0, s12
	s_sub_i32 s1, s4, s1
	s_xor_b32 s3, s3, s13
	s_add_i32 s4, s0, 1
	s_sub_i32 s5, s1, s12
	s_cmp_ge_u32 s1, s12
	s_cselect_b32 s0, s4, s0
	s_cselect_b32 s1, s5, s1
	s_add_i32 s4, s0, 1
	s_cmp_ge_u32 s1, s12
	s_cselect_b32 s0, s4, s0
	s_xor_b32 s0, s0, s3
	s_sub_i32 s3, s0, s3
	s_cmp_lt_i32 s22, 0
	s_cselect_b64 s[8:9], -1, 0
	s_and_b64 s[0:1], s[8:9], exec
	s_cselect_b32 s26, s3, s2
	s_not_b32 s0, s14
	s_lshr_b32 s0, s0, 31
	s_add_i32 s26, s26, s0
	s_cmp_lt_i32 s26, 1
	s_cbranch_scc1 .LBB0_476
	s_lshr_b32 s27, s10, 3
	s_cmp_lt_i32 s14, 0
	s_mul_hi_u32 s0, s14, 0x3521cfb3
	s_cselect_b64 s[10:11], -1, 0
	s_sub_i32 s2, s14, s0
	s_lshr_b32 s2, s2, 1
	s_add_i32 s2, s2, s0
	s_lshr_b32 s0, s2, 5
	s_add_i32 s28, s0, 0x80
	s_mul_i32 s0, s0, 53
	v_and_b32_e32 v2, 15, v0
	s_sub_i32 s29, s14, s0
	v_ashrrev_i32_e32 v3, 1, v0
	s_movk_i32 s0, 0xffc0
	v_and_or_b32 v87, v3, s0, v2
	v_lshrrev_b32_e32 v2, 2, v0
	v_and_b32_e32 v2, 12, v2
	v_and_or_b32 v86, v0, 64, v2
	v_and_b32_e32 v0, 64, v0
	v_cmp_ne_u32_e64 s[40:41], 0, v0
	v_or_b32_e32 v0, 16, v86
	v_cmp_gt_u32_e64 s[44:45], 40, v0
	v_or_b32_e32 v0, 32, v86
	v_cmp_gt_u32_e64 s[4:5], 40, v0
	v_cvt_f32_u32_e32 v0, s25
	v_readlane_b32 s2, v249, 52
	s_load_dwordx2 s[12:13], s[6:7], 0x138
	s_load_dwordx2 s[14:15], s[6:7], 0xe0
	s_lshl_b32 s0, s2, 8
	v_rcp_iflag_f32_e32 v0, v0
	s_or_b32 s30, s0, 0xffffc000
	s_sub_i32 s0, 0, s25
	s_mov_b32 s18, s2
	v_mul_f32_e32 v0, 0x4f7ffffe, v0
	v_cvt_u32_f32_e32 v0, v0
	v_readlane_b32 s3, v249, 53
	s_mul_i32 s72, s2, 0xc00
	s_lshl_b32 s31, s2, 14
	v_readfirstlane_b32 s16, v0
	s_mul_i32 s0, s0, s16
	s_mul_hi_u32 s0, s16, s0
	s_lshl_b32 s2, s2, 6
	s_add_i32 s33, s16, s0
	s_mul_i32 s16, s18, 0xd40000
	s_mov_b32 s3, s73
	s_mul_hi_u32 s0, s18, 0xd40000
	s_waitcnt lgkmcnt(0)
	s_add_u32 s34, s14, s16
	s_mov_b32 s1, 0
	v_or_b32_e32 v104, 0xfffff180, v86
	v_cmp_gt_u32_e64 s[42:43], 40, v86
	s_addc_u32 s35, s15, s0
	s_lshl_b64 s[16:17], s[72:73], 2
	s_lshl_b64 s[18:19], s[2:3], 2
	v_lshlrev_b32_e32 v105, 2, v2
	s_mov_b32 s32, 0
	v_readlane_b32 s2, v249, 1
	s_nop 0
	s_cmpk_lg_u32 s2, 0x200
	s_cbranch_scc1 .LBB0_212
	s_mov_b32 s48, 0
.Lg2_tile:
	v_readlane_b32 s2, v249, 0
	s_nop 0
	s_and_b32 s3, s2, 7
	s_lshr_b32 s2, s2, 3
	s_cmp_lt_u32 s2, 40
	s_cselect_b32 s38, 7, 6
	s_cmp_lt_u32 s48, s38
	s_cbranch_scc0 .Lg2_extra
	s_lshl_b32 s20, s48, 6
	s_add_i32 s20, s20, s2
	s_cmp_ge_u32 s20, 0xd4
	s_cselect_b32 s21, 1, 0
	s_mul_i32 s0, s21, 0xd4
	s_sub_i32 s20, s20, s0
	s_lshr_b32 s37, s20, 2
	s_and_b32 s20, s20, 3
	s_lshl_b32 s21, s21, 3
	s_add_i32 s20, s20, s21
	s_lshl_b32 s20, s20, 3
	s_add_i32 s0, s20, s3
	s_add_i32 s49, s0, 32
	s_branch .Lg2_go
.Lg2_extra:
	s_cmp_eq_u32 s48, s38
	s_cbranch_scc0 .Lg2_done
	s_cmp_lt_u32 s2, 40
	s_cbranch_scc1 .Lg2_done
	s_sub_i32 s20, s2, 40
	s_lshl_b32 s20, s20, 3
	s_add_i32 s37, s20, s3
	s_cmp_lt_u32 s37, 53
	s_cbranch_scc0 .Lg2_done
	s_movk_i32 s0, 0x80
	s_movk_i32 s49, 0x81
.Lg2_go:
	s_lshl_b32 s72, s37, 7
	v_and_b32_e32 v70, 7, v196
	v_bfe_u32 v71, v196, 4, 2
	v_bfe_u32 v72, v196, 6, 1
	v_lshl_or_b32 v73, v72, 2, v71
	v_xor_b32_e32 v70, v70, v73
	v_lshrrev_b32_e32 v73, 3, v196
	v_lshlrev_b32_e32 v73, 11, v73
	v_lshl_or_b32 v74, v70, 4, v73
	v_add_u32_e32 v75, 0x10000, v74
	v_add_u32_e32 v76, 0x20000, v74
	v_add_u32_e32 v77, 0x30000, v74
	v_and_b32_e32 v70, 15, v196
	v_bfe_u32 v73, v196, 1, 3
	v_xor_b32_e32 v73, v71, v73
	v_lshlrev_b32_e32 v73, 4, v73
	v_xor_b32_e32 v83, 64, v73
	v_lshlrev_b32_e32 v70, 7, v70
	v_lshrrev_b32_e32 v84, 7, v196
	v_lshl_or_b32 v84, v84, 13, v70
	v_lshl_or_b32 v85, v72, 13, v70
	v_add_u32_e32 v78, v84, v73
	v_add_u32_e32 v80, v84, v83
	v_add_u32_e32 v79, v85, v73
	v_add_u32_e32 v81, v85, v83
	v_readfirstlane_b32 s58, v196
	s_lshr_b32 s58, s58, 6
	s_lshl_b32 s58, s58, 10
	s_lshl_b32 s2, s0, 18
	s_add_u32 s50, s12, s2
	s_addc_u32 s51, s13, 0
	s_lshl_b32 s2, s49, 18
	s_add_u32 s52, s12, s2
	s_addc_u32 s53, s13, 0
	s_lshl_b32 s2, s37, 18
	s_add_u32 s56, s34, s2
	s_addc_u32 s57, s35, 0
	s_barrier
	s_add_i32 m0, s58, 0x0
	s_nop 0
	global_load_lds_dwordx4 v74, s[50:51]
	s_add_i32 m0, s58, 0x1000
	s_nop 0
	global_load_lds_dwordx4 v75, s[50:51]
	s_add_i32 m0, s58, 0x2000
	s_nop 0
	global_load_lds_dwordx4 v76, s[50:51]
	s_add_i32 m0, s58, 0x3000
	s_nop 0
	global_load_lds_dwordx4 v77, s[50:51]
	s_add_i32 m0, s58, 0x4000
	s_nop 0
	global_load_lds_dwordx4 v74, s[52:53]
	s_add_i32 m0, s58, 0x5000
	s_nop 0
	global_load_lds_dwordx4 v75, s[52:53]
	s_add_i32 m0, s58, 0x6000
	s_nop 0
	global_load_lds_dwordx4 v76, s[52:53]
	s_add_i32 m0, s58, 0x7000
	s_nop 0
	global_load_lds_dwordx4 v77, s[52:53]
	s_add_u32 s50, s50, 0x80
	s_addc_u32 s51, s51, 0
	s_add_u32 s52, s52, 0x80
	s_addc_u32 s53, s53, 0
	s_add_i32 m0, s58, 0x8000
	s_nop 0
	global_load_lds_dwordx4 v74, s[56:57]
	s_add_i32 m0, s58, 0x9000
	s_nop 0
	global_load_lds_dwordx4 v75, s[56:57]
	s_add_i32 m0, s58, 0xa000
	s_nop 0
	global_load_lds_dwordx4 v76, s[56:57]
	s_add_i32 m0, s58, 0xb000
	s_nop 0
	global_load_lds_dwordx4 v77, s[56:57]
	s_add_u32 s56, s56, 0x80
	s_addc_u32 s57, s57, 0
	v_mov_b64_e32 v[62:63], 0
	v_mov_b64_e32 v[64:65], 0
	v_mov_b64_e32 v[58:59], 0
	v_mov_b64_e32 v[60:61], 0
	v_mov_b64_e32 v[54:55], 0
	v_mov_b64_e32 v[56:57], 0
	v_mov_b64_e32 v[50:51], 0
	v_mov_b64_e32 v[52:53], 0
	v_mov_b64_e32 v[46:47], 0
	v_mov_b64_e32 v[48:49], 0
	v_mov_b64_e32 v[42:43], 0
	v_mov_b64_e32 v[44:45], 0
	v_mov_b64_e32 v[38:39], 0
	v_mov_b64_e32 v[40:41], 0
	v_mov_b64_e32 v[34:35], 0
	v_mov_b64_e32 v[36:37], 0
	v_mov_b64_e32 v[30:31], 0
	v_mov_b64_e32 v[32:33], 0
	v_mov_b64_e32 v[26:27], 0
	v_mov_b64_e32 v[28:29], 0
	v_mov_b64_e32 v[22:23], 0
	v_mov_b64_e32 v[24:25], 0
	v_mov_b64_e32 v[18:19], 0
	v_mov_b64_e32 v[20:21], 0
	v_mov_b64_e32 v[14:15], 0
	v_mov_b64_e32 v[16:17], 0
	v_mov_b64_e32 v[10:11], 0
	v_mov_b64_e32 v[12:13], 0
	v_mov_b64_e32 v[6:7], 0
	v_mov_b64_e32 v[8:9], 0
	v_mov_b64_e32 v[2:3], 0
	v_mov_b64_e32 v[4:5], 0
	v_mov_b64_e32 v[66:67], 0
	v_mov_b64_e32 v[68:69], 0
	v_mov_b64_e32 v[70:71], 0
	v_mov_b64_e32 v[72:73], 0
	v_mov_b64_e32 v[82:83], 0
	v_mov_b64_e32 v[84:85], 0
	v_mov_b64_e32 v[88:89], 0
	v_mov_b64_e32 v[90:91], 0
	v_mov_b64_e32 v[92:93], 0
	v_mov_b64_e32 v[94:95], 0
	v_mov_b64_e32 v[96:97], 0
	v_mov_b64_e32 v[98:99], 0
	v_mov_b64_e32 v[100:101], 0
	v_mov_b64_e32 v[102:103], 0
	v_mov_b64_e32 v[106:107], 0
	v_mov_b64_e32 v[108:109], 0
	v_mov_b64_e32 v[110:111], 0
	v_mov_b64_e32 v[112:113], 0
	v_mov_b64_e32 v[114:115], 0
	v_mov_b64_e32 v[116:117], 0
	v_mov_b64_e32 v[118:119], 0
	v_mov_b64_e32 v[120:121], 0
	v_mov_b64_e32 v[122:123], 0
	v_mov_b64_e32 v[124:125], 0
	v_mov_b64_e32 v[126:127], 0
	v_mov_b64_e32 v[128:129], 0
	v_mov_b64_e32 v[136:137], 0
	v_mov_b64_e32 v[138:139], 0
	v_mov_b64_e32 v[140:141], 0
	v_mov_b64_e32 v[142:143], 0
	v_mov_b64_e32 v[144:145], 0
	v_mov_b64_e32 v[146:147], 0
	s_movk_i32 s59, 7
.Lg2_k:
	s_waitcnt vmcnt(0)
	s_barrier
	s_add_i32 m0, s58, 0xc000
	s_nop 0
	global_load_lds_dwordx4 v74, s[56:57]
	s_add_i32 m0, s58, 0xd000
	s_nop 0
	global_load_lds_dwordx4 v75, s[56:57]
	s_add_i32 m0, s58, 0xe000
	s_nop 0
	global_load_lds_dwordx4 v76, s[56:57]
	s_add_i32 m0, s58, 0xf000
	s_nop 0
	global_load_lds_dwordx4 v77, s[56:57]
	s_add_u32 s56, s56, 0x80
	s_addc_u32 s57, s57, 0
	ds_read_b128 v[148:151], v78 offset:0
	ds_read_b128 v[152:155], v78 offset:2048
	ds_read_b128 v[156:159], v78 offset:4096
	ds_read_b128 v[160:163], v78 offset:6144
	ds_read_b128 v[164:167], v78 offset:16384
	ds_read_b128 v[168:171], v78 offset:18432
	ds_read_b128 v[174:177], v78 offset:20480
	ds_read_b128 v[182:185], v78 offset:22528
	ds_read_b128 v[188:191], v79 offset:32768
	ds_read_b128 v[192:195], v79 offset:34816
	ds_read_b128 v[208:211], v79 offset:36864
	ds_read_b128 v[212:215], v79 offset:38912
	s_waitcnt lgkmcnt(0)
	s_setprio 1
	v_mfma_f32_16x16x32_bf16 v[62:65], v[188:191], v[148:151], v[62:65]
	v_mfma_f32_16x16x32_bf16 v[58:61], v[192:195], v[148:151], v[58:61]
	v_mfma_f32_16x16x32_bf16 v[54:57], v[208:211], v[148:151], v[54:57]
	v_mfma_f32_16x16x32_bf16 v[50:53], v[212:215], v[148:151], v[50:53]
	v_mfma_f32_16x16x32_bf16 v[46:49], v[188:191], v[152:155], v[46:49]
	v_mfma_f32_16x16x32_bf16 v[42:45], v[192:195], v[152:155], v[42:45]
	v_mfma_f32_16x16x32_bf16 v[38:41], v[208:211], v[152:155], v[38:41]
	v_mfma_f32_16x16x32_bf16 v[34:37], v[212:215], v[152:155], v[34:37]
	v_mfma_f32_16x16x32_bf16 v[30:33], v[188:191], v[156:159], v[30:33]
	v_mfma_f32_16x16x32_bf16 v[26:29], v[192:195], v[156:159], v[26:29]
	v_mfma_f32_16x16x32_bf16 v[22:25], v[208:211], v[156:159], v[22:25]
	v_mfma_f32_16x16x32_bf16 v[18:21], v[212:215], v[156:159], v[18:21]
	v_mfma_f32_16x16x32_bf16 v[14:17], v[188:191], v[160:163], v[14:17]
	v_mfma_f32_16x16x32_bf16 v[10:13], v[192:195], v[160:163], v[10:13]
	v_mfma_f32_16x16x32_bf16 v[6:9], v[208:211], v[160:163], v[6:9]
	v_mfma_f32_16x16x32_bf16 v[2:5], v[212:215], v[160:163], v[2:5]
	v_mfma_f32_16x16x32_bf16 v[66:69], v[188:191], v[164:167], v[66:69]
	v_mfma_f32_16x16x32_bf16 v[70:73], v[192:195], v[164:167], v[70:73]
	v_mfma_f32_16x16x32_bf16 v[82:85], v[208:211], v[164:167], v[82:85]
	v_mfma_f32_16x16x32_bf16 v[88:91], v[212:215], v[164:167], v[88:91]
	v_mfma_f32_16x16x32_bf16 v[92:95], v[188:191], v[168:171], v[92:95]
	v_mfma_f32_16x16x32_bf16 v[96:99], v[192:195], v[168:171], v[96:99]
	v_mfma_f32_16x16x32_bf16 v[100:103], v[208:211], v[168:171], v[100:103]
	v_mfma_f32_16x16x32_bf16 v[106:109], v[212:215], v[168:171], v[106:109]
	v_mfma_f32_16x16x32_bf16 v[110:113], v[188:191], v[174:177], v[110:113]
	v_mfma_f32_16x16x32_bf16 v[114:117], v[192:195], v[174:177], v[114:117]
	v_mfma_f32_16x16x32_bf16 v[118:121], v[208:211], v[174:177], v[118:121]
	v_mfma_f32_16x16x32_bf16 v[122:125], v[212:215], v[174:177], v[122:125]
	v_mfma_f32_16x16x32_bf16 v[126:129], v[188:191], v[182:185], v[126:129]
	v_mfma_f32_16x16x32_bf16 v[136:139], v[192:195], v[182:185], v[136:139]
	v_mfma_f32_16x16x32_bf16 v[140:143], v[208:211], v[182:185], v[140:143]
	v_mfma_f32_16x16x32_bf16 v[144:147], v[212:215], v[182:185], v[144:147]
	s_setprio 0
	ds_read_b128 v[148:151], v80 offset:0
	ds_read_b128 v[152:155], v80 offset:2048
	ds_read_b128 v[156:159], v80 offset:4096
	ds_read_b128 v[160:163], v80 offset:6144
	ds_read_b128 v[164:167], v80 offset:16384
	ds_read_b128 v[168:171], v80 offset:18432
	ds_read_b128 v[174:177], v80 offset:20480
	ds_read_b128 v[182:185], v80 offset:22528
	ds_read_b128 v[188:191], v81 offset:32768
	ds_read_b128 v[192:195], v81 offset:34816
	ds_read_b128 v[208:211], v81 offset:36864
	ds_read_b128 v[212:215], v81 offset:38912
	s_waitcnt lgkmcnt(0)
	s_barrier
	s_add_i32 m0, s58, 0x0
	s_nop 0
	global_load_lds_dwordx4 v74, s[50:51]
	s_add_i32 m0, s58, 0x1000
	s_nop 0
	global_load_lds_dwordx4 v75, s[50:51]
	s_add_i32 m0, s58, 0x2000
	s_nop 0
	global_load_lds_dwordx4 v76, s[50:51]
	s_add_i32 m0, s58, 0x3000
	s_nop 0
	global_load_lds_dwordx4 v77, s[50:51]
	s_add_i32 m0, s58, 0x4000
	s_nop 0
	global_load_lds_dwordx4 v74, s[52:53]
	s_add_i32 m0, s58, 0x5000
	s_nop 0
	global_load_lds_dwordx4 v75, s[52:53]
	s_add_i32 m0, s58, 0x6000
	s_nop 0
	global_load_lds_dwordx4 v76, s[52:53]
	s_add_i32 m0, s58, 0x7000
	s_nop 0
	global_load_lds_dwordx4 v77, s[52:53]
	s_add_u32 s50, s50, 0x80
	s_addc_u32 s51, s51, 0
	s_add_u32 s52, s52, 0x80
	s_addc_u32 s53, s53, 0
	s_setprio 1
	v_mfma_f32_16x16x32_bf16 v[62:65], v[188:191], v[148:151], v[62:65]
	v_mfma_f32_16x16x32_bf16 v[58:61], v[192:195], v[148:151], v[58:61]
	v_mfma_f32_16x16x32_bf16 v[54:57], v[208:211], v[148:151], v[54:57]
	v_mfma_f32_16x16x32_bf16 v[50:53], v[212:215], v[148:151], v[50:53]
	v_mfma_f32_16x16x32_bf16 v[46:49], v[188:191], v[152:155], v[46:49]
	v_mfma_f32_16x16x32_bf16 v[42:45], v[192:195], v[152:155], v[42:45]
	v_mfma_f32_16x16x32_bf16 v[38:41], v[208:211], v[152:155], v[38:41]
	v_mfma_f32_16x16x32_bf16 v[34:37], v[212:215], v[152:155], v[34:37]
	v_mfma_f32_16x16x32_bf16 v[30:33], v[188:191], v[156:159], v[30:33]
	v_mfma_f32_16x16x32_bf16 v[26:29], v[192:195], v[156:159], v[26:29]
	v_mfma_f32_16x16x32_bf16 v[22:25], v[208:211], v[156:159], v[22:25]
	v_mfma_f32_16x16x32_bf16 v[18:21], v[212:215], v[156:159], v[18:21]
	v_mfma_f32_16x16x32_bf16 v[14:17], v[188:191], v[160:163], v[14:17]
	v_mfma_f32_16x16x32_bf16 v[10:13], v[192:195], v[160:163], v[10:13]
	v_mfma_f32_16x16x32_bf16 v[6:9], v[208:211], v[160:163], v[6:9]
	v_mfma_f32_16x16x32_bf16 v[2:5], v[212:215], v[160:163], v[2:5]
	v_mfma_f32_16x16x32_bf16 v[66:69], v[188:191], v[164:167], v[66:69]
	v_mfma_f32_16x16x32_bf16 v[70:73], v[192:195], v[164:167], v[70:73]
	v_mfma_f32_16x16x32_bf16 v[82:85], v[208:211], v[164:167], v[82:85]
	v_mfma_f32_16x16x32_bf16 v[88:91], v[212:215], v[164:167], v[88:91]
	v_mfma_f32_16x16x32_bf16 v[92:95], v[188:191], v[168:171], v[92:95]
	v_mfma_f32_16x16x32_bf16 v[96:99], v[192:195], v[168:171], v[96:99]
	v_mfma_f32_16x16x32_bf16 v[100:103], v[208:211], v[168:171], v[100:103]
	v_mfma_f32_16x16x32_bf16 v[106:109], v[212:215], v[168:171], v[106:109]
	v_mfma_f32_16x16x32_bf16 v[110:113], v[188:191], v[174:177], v[110:113]
	v_mfma_f32_16x16x32_bf16 v[114:117], v[192:195], v[174:177], v[114:117]
	v_mfma_f32_16x16x32_bf16 v[118:121], v[208:211], v[174:177], v[118:121]
	v_mfma_f32_16x16x32_bf16 v[122:125], v[212:215], v[174:177], v[122:125]
	v_mfma_f32_16x16x32_bf16 v[126:129], v[188:191], v[182:185], v[126:129]
	v_mfma_f32_16x16x32_bf16 v[136:139], v[192:195], v[182:185], v[136:139]
	v_mfma_f32_16x16x32_bf16 v[140:143], v[208:211], v[182:185], v[140:143]
	v_mfma_f32_16x16x32_bf16 v[144:147], v[212:215], v[182:185], v[144:147]
	s_setprio 0
	s_waitcnt vmcnt(0)
	s_barrier
	s_add_i32 m0, s58, 0x8000
	s_nop 0
	global_load_lds_dwordx4 v74, s[56:57]
	s_add_i32 m0, s58, 0x9000
	s_nop 0
	global_load_lds_dwordx4 v75, s[56:57]
	s_add_i32 m0, s58, 0xa000
	s_nop 0
	global_load_lds_dwordx4 v76, s[56:57]
	s_add_i32 m0, s58, 0xb000
	s_nop 0
	global_load_lds_dwordx4 v77, s[56:57]
	s_add_u32 s56, s56, 0x80
	s_addc_u32 s57, s57, 0
	ds_read_b128 v[148:151], v78 offset:0
	ds_read_b128 v[152:155], v78 offset:2048
	ds_read_b128 v[156:159], v78 offset:4096
	ds_read_b128 v[160:163], v78 offset:6144
	ds_read_b128 v[164:167], v78 offset:16384
	ds_read_b128 v[168:171], v78 offset:18432
	ds_read_b128 v[174:177], v78 offset:20480
	ds_read_b128 v[182:185], v78 offset:22528
	ds_read_b128 v[188:191], v79 offset:49152
	ds_read_b128 v[192:195], v79 offset:51200
	ds_read_b128 v[208:211], v79 offset:53248
	ds_read_b128 v[212:215], v79 offset:55296
	s_waitcnt lgkmcnt(0)
	s_setprio 1
	v_mfma_f32_16x16x32_bf16 v[62:65], v[188:191], v[148:151], v[62:65]
	v_mfma_f32_16x16x32_bf16 v[58:61], v[192:195], v[148:151], v[58:61]
	v_mfma_f32_16x16x32_bf16 v[54:57], v[208:211], v[148:151], v[54:57]
	v_mfma_f32_16x16x32_bf16 v[50:53], v[212:215], v[148:151], v[50:53]
	v_mfma_f32_16x16x32_bf16 v[46:49], v[188:191], v[152:155], v[46:49]
	v_mfma_f32_16x16x32_bf16 v[42:45], v[192:195], v[152:155], v[42:45]
	v_mfma_f32_16x16x32_bf16 v[38:41], v[208:211], v[152:155], v[38:41]
	v_mfma_f32_16x16x32_bf16 v[34:37], v[212:215], v[152:155], v[34:37]
	v_mfma_f32_16x16x32_bf16 v[30:33], v[188:191], v[156:159], v[30:33]
	v_mfma_f32_16x16x32_bf16 v[26:29], v[192:195], v[156:159], v[26:29]
	v_mfma_f32_16x16x32_bf16 v[22:25], v[208:211], v[156:159], v[22:25]
	v_mfma_f32_16x16x32_bf16 v[18:21], v[212:215], v[156:159], v[18:21]
	v_mfma_f32_16x16x32_bf16 v[14:17], v[188:191], v[160:163], v[14:17]
	v_mfma_f32_16x16x32_bf16 v[10:13], v[192:195], v[160:163], v[10:13]
	v_mfma_f32_16x16x32_bf16 v[6:9], v[208:211], v[160:163], v[6:9]
	v_mfma_f32_16x16x32_bf16 v[2:5], v[212:215], v[160:163], v[2:5]
	v_mfma_f32_16x16x32_bf16 v[66:69], v[188:191], v[164:167], v[66:69]
	v_mfma_f32_16x16x32_bf16 v[70:73], v[192:195], v[164:167], v[70:73]
	v_mfma_f32_16x16x32_bf16 v[82:85], v[208:211], v[164:167], v[82:85]
	v_mfma_f32_16x16x32_bf16 v[88:91], v[212:215], v[164:167], v[88:91]
	v_mfma_f32_16x16x32_bf16 v[92:95], v[188:191], v[168:171], v[92:95]
	v_mfma_f32_16x16x32_bf16 v[96:99], v[192:195], v[168:171], v[96:99]
	v_mfma_f32_16x16x32_bf16 v[100:103], v[208:211], v[168:171], v[100:103]
	v_mfma_f32_16x16x32_bf16 v[106:109], v[212:215], v[168:171], v[106:109]
	v_mfma_f32_16x16x32_bf16 v[110:113], v[188:191], v[174:177], v[110:113]
	v_mfma_f32_16x16x32_bf16 v[114:117], v[192:195], v[174:177], v[114:117]
	v_mfma_f32_16x16x32_bf16 v[118:121], v[208:211], v[174:177], v[118:121]
	v_mfma_f32_16x16x32_bf16 v[122:125], v[212:215], v[174:177], v[122:125]
	v_mfma_f32_16x16x32_bf16 v[126:129], v[188:191], v[182:185], v[126:129]
	v_mfma_f32_16x16x32_bf16 v[136:139], v[192:195], v[182:185], v[136:139]
	v_mfma_f32_16x16x32_bf16 v[140:143], v[208:211], v[182:185], v[140:143]
	v_mfma_f32_16x16x32_bf16 v[144:147], v[212:215], v[182:185], v[144:147]
	s_setprio 0
	ds_read_b128 v[148:151], v80 offset:0
	ds_read_b128 v[152:155], v80 offset:2048
	ds_read_b128 v[156:159], v80 offset:4096
	ds_read_b128 v[160:163], v80 offset:6144
	ds_read_b128 v[164:167], v80 offset:16384
	ds_read_b128 v[168:171], v80 offset:18432
	ds_read_b128 v[174:177], v80 offset:20480
	ds_read_b128 v[182:185], v80 offset:22528
	ds_read_b128 v[188:191], v81 offset:49152
	ds_read_b128 v[192:195], v81 offset:51200
	ds_read_b128 v[208:211], v81 offset:53248
	ds_read_b128 v[212:215], v81 offset:55296
	s_waitcnt lgkmcnt(0)
	s_barrier
	s_add_i32 m0, s58, 0x0
	s_nop 0
	global_load_lds_dwordx4 v74, s[50:51]
	s_add_i32 m0, s58, 0x1000
	s_nop 0
	global_load_lds_dwordx4 v75, s[50:51]
	s_add_i32 m0, s58, 0x2000
	s_nop 0
	global_load_lds_dwordx4 v76, s[50:51]
	s_add_i32 m0, s58, 0x3000
	s_nop 0
	global_load_lds_dwordx4 v77, s[50:51]
	s_add_i32 m0, s58, 0x4000
	s_nop 0
	global_load_lds_dwordx4 v74, s[52:53]
	s_add_i32 m0, s58, 0x5000
	s_nop 0
	global_load_lds_dwordx4 v75, s[52:53]
	s_add_i32 m0, s58, 0x6000
	s_nop 0
	global_load_lds_dwordx4 v76, s[52:53]
	s_add_i32 m0, s58, 0x7000
	s_nop 0
	global_load_lds_dwordx4 v77, s[52:53]
	s_add_u32 s50, s50, 0x80
	s_addc_u32 s51, s51, 0
	s_add_u32 s52, s52, 0x80
	s_addc_u32 s53, s53, 0
	s_setprio 1
	v_mfma_f32_16x16x32_bf16 v[62:65], v[188:191], v[148:151], v[62:65]
	v_mfma_f32_16x16x32_bf16 v[58:61], v[192:195], v[148:151], v[58:61]
	v_mfma_f32_16x16x32_bf16 v[54:57], v[208:211], v[148:151], v[54:57]
	v_mfma_f32_16x16x32_bf16 v[50:53], v[212:215], v[148:151], v[50:53]
	v_mfma_f32_16x16x32_bf16 v[46:49], v[188:191], v[152:155], v[46:49]
	v_mfma_f32_16x16x32_bf16 v[42:45], v[192:195], v[152:155], v[42:45]
	v_mfma_f32_16x16x32_bf16 v[38:41], v[208:211], v[152:155], v[38:41]
	v_mfma_f32_16x16x32_bf16 v[34:37], v[212:215], v[152:155], v[34:37]
	v_mfma_f32_16x16x32_bf16 v[30:33], v[188:191], v[156:159], v[30:33]
	v_mfma_f32_16x16x32_bf16 v[26:29], v[192:195], v[156:159], v[26:29]
	v_mfma_f32_16x16x32_bf16 v[22:25], v[208:211], v[156:159], v[22:25]
	v_mfma_f32_16x16x32_bf16 v[18:21], v[212:215], v[156:159], v[18:21]
	v_mfma_f32_16x16x32_bf16 v[14:17], v[188:191], v[160:163], v[14:17]
	v_mfma_f32_16x16x32_bf16 v[10:13], v[192:195], v[160:163], v[10:13]
	v_mfma_f32_16x16x32_bf16 v[6:9], v[208:211], v[160:163], v[6:9]
	v_mfma_f32_16x16x32_bf16 v[2:5], v[212:215], v[160:163], v[2:5]
	v_mfma_f32_16x16x32_bf16 v[66:69], v[188:191], v[164:167], v[66:69]
	v_mfma_f32_16x16x32_bf16 v[70:73], v[192:195], v[164:167], v[70:73]
	v_mfma_f32_16x16x32_bf16 v[82:85], v[208:211], v[164:167], v[82:85]
	v_mfma_f32_16x16x32_bf16 v[88:91], v[212:215], v[164:167], v[88:91]
	v_mfma_f32_16x16x32_bf16 v[92:95], v[188:191], v[168:171], v[92:95]
	v_mfma_f32_16x16x32_bf16 v[96:99], v[192:195], v[168:171], v[96:99]
	v_mfma_f32_16x16x32_bf16 v[100:103], v[208:211], v[168:171], v[100:103]
	v_mfma_f32_16x16x32_bf16 v[106:109], v[212:215], v[168:171], v[106:109]
	v_mfma_f32_16x16x32_bf16 v[110:113], v[188:191], v[174:177], v[110:113]
	v_mfma_f32_16x16x32_bf16 v[114:117], v[192:195], v[174:177], v[114:117]
	v_mfma_f32_16x16x32_bf16 v[118:121], v[208:211], v[174:177], v[118:121]
	v_mfma_f32_16x16x32_bf16 v[122:125], v[212:215], v[174:177], v[122:125]
	v_mfma_f32_16x16x32_bf16 v[126:129], v[188:191], v[182:185], v[126:129]
	v_mfma_f32_16x16x32_bf16 v[136:139], v[192:195], v[182:185], v[136:139]
	v_mfma_f32_16x16x32_bf16 v[140:143], v[208:211], v[182:185], v[140:143]
	v_mfma_f32_16x16x32_bf16 v[144:147], v[212:215], v[182:185], v[144:147]
	s_setprio 0
	s_add_i32 s59, s59, -1
	s_cmp_lg_u32 s59, 0
	s_cbranch_scc1 .Lg2_k
	s_waitcnt vmcnt(0)
	s_barrier
	s_add_i32 m0, s58, 0xc000
	s_nop 0
	global_load_lds_dwordx4 v74, s[56:57]
	s_add_i32 m0, s58, 0xd000
	s_nop 0
	global_load_lds_dwordx4 v75, s[56:57]
	s_add_i32 m0, s58, 0xe000
	s_nop 0
	global_load_lds_dwordx4 v76, s[56:57]
	s_add_i32 m0, s58, 0xf000
	s_nop 0
	global_load_lds_dwordx4 v77, s[56:57]
	s_add_u32 s56, s56, 0x80
	s_addc_u32 s57, s57, 0
	ds_read_b128 v[148:151], v78 offset:0
	ds_read_b128 v[152:155], v78 offset:2048
	ds_read_b128 v[156:159], v78 offset:4096
	ds_read_b128 v[160:163], v78 offset:6144
	ds_read_b128 v[164:167], v78 offset:16384
	ds_read_b128 v[168:171], v78 offset:18432
	ds_read_b128 v[174:177], v78 offset:20480
	ds_read_b128 v[182:185], v78 offset:22528
	ds_read_b128 v[188:191], v79 offset:32768
	ds_read_b128 v[192:195], v79 offset:34816
	ds_read_b128 v[208:211], v79 offset:36864
	ds_read_b128 v[212:215], v79 offset:38912
	s_waitcnt lgkmcnt(0)
	s_setprio 1
	v_mfma_f32_16x16x32_bf16 v[62:65], v[188:191], v[148:151], v[62:65]
	v_mfma_f32_16x16x32_bf16 v[58:61], v[192:195], v[148:151], v[58:61]
	v_mfma_f32_16x16x32_bf16 v[54:57], v[208:211], v[148:151], v[54:57]
	v_mfma_f32_16x16x32_bf16 v[50:53], v[212:215], v[148:151], v[50:53]
	v_mfma_f32_16x16x32_bf16 v[46:49], v[188:191], v[152:155], v[46:49]
	v_mfma_f32_16x16x32_bf16 v[42:45], v[192:195], v[152:155], v[42:45]
	v_mfma_f32_16x16x32_bf16 v[38:41], v[208:211], v[152:155], v[38:41]
	v_mfma_f32_16x16x32_bf16 v[34:37], v[212:215], v[152:155], v[34:37]
	v_mfma_f32_16x16x32_bf16 v[30:33], v[188:191], v[156:159], v[30:33]
	v_mfma_f32_16x16x32_bf16 v[26:29], v[192:195], v[156:159], v[26:29]
	v_mfma_f32_16x16x32_bf16 v[22:25], v[208:211], v[156:159], v[22:25]
	v_mfma_f32_16x16x32_bf16 v[18:21], v[212:215], v[156:159], v[18:21]
	v_mfma_f32_16x16x32_bf16 v[14:17], v[188:191], v[160:163], v[14:17]
	v_mfma_f32_16x16x32_bf16 v[10:13], v[192:195], v[160:163], v[10:13]
	v_mfma_f32_16x16x32_bf16 v[6:9], v[208:211], v[160:163], v[6:9]
	v_mfma_f32_16x16x32_bf16 v[2:5], v[212:215], v[160:163], v[2:5]
	v_mfma_f32_16x16x32_bf16 v[66:69], v[188:191], v[164:167], v[66:69]
	v_mfma_f32_16x16x32_bf16 v[70:73], v[192:195], v[164:167], v[70:73]
	v_mfma_f32_16x16x32_bf16 v[82:85], v[208:211], v[164:167], v[82:85]
	v_mfma_f32_16x16x32_bf16 v[88:91], v[212:215], v[164:167], v[88:91]
	v_mfma_f32_16x16x32_bf16 v[92:95], v[188:191], v[168:171], v[92:95]
	v_mfma_f32_16x16x32_bf16 v[96:99], v[192:195], v[168:171], v[96:99]
	v_mfma_f32_16x16x32_bf16 v[100:103], v[208:211], v[168:171], v[100:103]
	v_mfma_f32_16x16x32_bf16 v[106:109], v[212:215], v[168:171], v[106:109]
	v_mfma_f32_16x16x32_bf16 v[110:113], v[188:191], v[174:177], v[110:113]
	v_mfma_f32_16x16x32_bf16 v[114:117], v[192:195], v[174:177], v[114:117]
	v_mfma_f32_16x16x32_bf16 v[118:121], v[208:211], v[174:177], v[118:121]
	v_mfma_f32_16x16x32_bf16 v[122:125], v[212:215], v[174:177], v[122:125]
	v_mfma_f32_16x16x32_bf16 v[126:129], v[188:191], v[182:185], v[126:129]
	v_mfma_f32_16x16x32_bf16 v[136:139], v[192:195], v[182:185], v[136:139]
	v_mfma_f32_16x16x32_bf16 v[140:143], v[208:211], v[182:185], v[140:143]
	v_mfma_f32_16x16x32_bf16 v[144:147], v[212:215], v[182:185], v[144:147]
	s_setprio 0
	ds_read_b128 v[148:151], v80 offset:0
	ds_read_b128 v[152:155], v80 offset:2048
	ds_read_b128 v[156:159], v80 offset:4096
	ds_read_b128 v[160:163], v80 offset:6144
	ds_read_b128 v[164:167], v80 offset:16384
	ds_read_b128 v[168:171], v80 offset:18432
	ds_read_b128 v[174:177], v80 offset:20480
	ds_read_b128 v[182:185], v80 offset:22528
	ds_read_b128 v[188:191], v81 offset:32768
	ds_read_b128 v[192:195], v81 offset:34816
	ds_read_b128 v[208:211], v81 offset:36864
	ds_read_b128 v[212:215], v81 offset:38912
	s_waitcnt lgkmcnt(0)
	s_barrier
	s_add_i32 m0, s58, 0x0
	s_nop 0
	global_load_lds_dwordx4 v74, s[50:51]
	s_add_i32 m0, s58, 0x1000
	s_nop 0
	global_load_lds_dwordx4 v75, s[50:51]
	s_add_i32 m0, s58, 0x2000
	s_nop 0
	global_load_lds_dwordx4 v76, s[50:51]
	s_add_i32 m0, s58, 0x3000
	s_nop 0
	global_load_lds_dwordx4 v77, s[50:51]
	s_add_i32 m0, s58, 0x4000
	s_nop 0
	global_load_lds_dwordx4 v74, s[52:53]
	s_add_i32 m0, s58, 0x5000
	s_nop 0
	global_load_lds_dwordx4 v75, s[52:53]
	s_add_i32 m0, s58, 0x6000
	s_nop 0
	global_load_lds_dwordx4 v76, s[52:53]
	s_add_i32 m0, s58, 0x7000
	s_nop 0
	global_load_lds_dwordx4 v77, s[52:53]
	s_add_u32 s50, s50, 0x80
	s_addc_u32 s51, s51, 0
	s_add_u32 s52, s52, 0x80
	s_addc_u32 s53, s53, 0
	s_setprio 1
	v_mfma_f32_16x16x32_bf16 v[62:65], v[188:191], v[148:151], v[62:65]
	v_mfma_f32_16x16x32_bf16 v[58:61], v[192:195], v[148:151], v[58:61]
	v_mfma_f32_16x16x32_bf16 v[54:57], v[208:211], v[148:151], v[54:57]
	v_mfma_f32_16x16x32_bf16 v[50:53], v[212:215], v[148:151], v[50:53]
	v_mfma_f32_16x16x32_bf16 v[46:49], v[188:191], v[152:155], v[46:49]
	v_mfma_f32_16x16x32_bf16 v[42:45], v[192:195], v[152:155], v[42:45]
	v_mfma_f32_16x16x32_bf16 v[38:41], v[208:211], v[152:155], v[38:41]
	v_mfma_f32_16x16x32_bf16 v[34:37], v[212:215], v[152:155], v[34:37]
	v_mfma_f32_16x16x32_bf16 v[30:33], v[188:191], v[156:159], v[30:33]
	v_mfma_f32_16x16x32_bf16 v[26:29], v[192:195], v[156:159], v[26:29]
	v_mfma_f32_16x16x32_bf16 v[22:25], v[208:211], v[156:159], v[22:25]
	v_mfma_f32_16x16x32_bf16 v[18:21], v[212:215], v[156:159], v[18:21]
	v_mfma_f32_16x16x32_bf16 v[14:17], v[188:191], v[160:163], v[14:17]
	v_mfma_f32_16x16x32_bf16 v[10:13], v[192:195], v[160:163], v[10:13]
	v_mfma_f32_16x16x32_bf16 v[6:9], v[208:211], v[160:163], v[6:9]
	v_mfma_f32_16x16x32_bf16 v[2:5], v[212:215], v[160:163], v[2:5]
	v_mfma_f32_16x16x32_bf16 v[66:69], v[188:191], v[164:167], v[66:69]
	v_mfma_f32_16x16x32_bf16 v[70:73], v[192:195], v[164:167], v[70:73]
	v_mfma_f32_16x16x32_bf16 v[82:85], v[208:211], v[164:167], v[82:85]
	v_mfma_f32_16x16x32_bf16 v[88:91], v[212:215], v[164:167], v[88:91]
	v_mfma_f32_16x16x32_bf16 v[92:95], v[188:191], v[168:171], v[92:95]
	v_mfma_f32_16x16x32_bf16 v[96:99], v[192:195], v[168:171], v[96:99]
	v_mfma_f32_16x16x32_bf16 v[100:103], v[208:211], v[168:171], v[100:103]
	v_mfma_f32_16x16x32_bf16 v[106:109], v[212:215], v[168:171], v[106:109]
	v_mfma_f32_16x16x32_bf16 v[110:113], v[188:191], v[174:177], v[110:113]
	v_mfma_f32_16x16x32_bf16 v[114:117], v[192:195], v[174:177], v[114:117]
	v_mfma_f32_16x16x32_bf16 v[118:121], v[208:211], v[174:177], v[118:121]
	v_mfma_f32_16x16x32_bf16 v[122:125], v[212:215], v[174:177], v[122:125]
	v_mfma_f32_16x16x32_bf16 v[126:129], v[188:191], v[182:185], v[126:129]
	v_mfma_f32_16x16x32_bf16 v[136:139], v[192:195], v[182:185], v[136:139]
	v_mfma_f32_16x16x32_bf16 v[140:143], v[208:211], v[182:185], v[140:143]
	v_mfma_f32_16x16x32_bf16 v[144:147], v[212:215], v[182:185], v[144:147]
	s_setprio 0
	s_waitcnt vmcnt(0)
	s_barrier
	ds_read_b128 v[148:151], v78 offset:0
	ds_read_b128 v[152:155], v78 offset:2048
	ds_read_b128 v[156:159], v78 offset:4096
	ds_read_b128 v[160:163], v78 offset:6144
	ds_read_b128 v[164:167], v78 offset:16384
	ds_read_b128 v[168:171], v78 offset:18432
	ds_read_b128 v[174:177], v78 offset:20480
	ds_read_b128 v[182:185], v78 offset:22528
	ds_read_b128 v[188:191], v79 offset:49152
	ds_read_b128 v[192:195], v79 offset:51200
	ds_read_b128 v[208:211], v79 offset:53248
	ds_read_b128 v[212:215], v79 offset:55296
	s_waitcnt lgkmcnt(0)
	s_setprio 1
	v_mfma_f32_16x16x32_bf16 v[62:65], v[188:191], v[148:151], v[62:65]
	v_mfma_f32_16x16x32_bf16 v[58:61], v[192:195], v[148:151], v[58:61]
	v_mfma_f32_16x16x32_bf16 v[54:57], v[208:211], v[148:151], v[54:57]
	v_mfma_f32_16x16x32_bf16 v[50:53], v[212:215], v[148:151], v[50:53]
	v_mfma_f32_16x16x32_bf16 v[46:49], v[188:191], v[152:155], v[46:49]
	v_mfma_f32_16x16x32_bf16 v[42:45], v[192:195], v[152:155], v[42:45]
	v_mfma_f32_16x16x32_bf16 v[38:41], v[208:211], v[152:155], v[38:41]
	v_mfma_f32_16x16x32_bf16 v[34:37], v[212:215], v[152:155], v[34:37]
	v_mfma_f32_16x16x32_bf16 v[30:33], v[188:191], v[156:159], v[30:33]
	v_mfma_f32_16x16x32_bf16 v[26:29], v[192:195], v[156:159], v[26:29]
	v_mfma_f32_16x16x32_bf16 v[22:25], v[208:211], v[156:159], v[22:25]
	v_mfma_f32_16x16x32_bf16 v[18:21], v[212:215], v[156:159], v[18:21]
	v_mfma_f32_16x16x32_bf16 v[14:17], v[188:191], v[160:163], v[14:17]
	v_mfma_f32_16x16x32_bf16 v[10:13], v[192:195], v[160:163], v[10:13]
	v_mfma_f32_16x16x32_bf16 v[6:9], v[208:211], v[160:163], v[6:9]
	v_mfma_f32_16x16x32_bf16 v[2:5], v[212:215], v[160:163], v[2:5]
	v_mfma_f32_16x16x32_bf16 v[66:69], v[188:191], v[164:167], v[66:69]
	v_mfma_f32_16x16x32_bf16 v[70:73], v[192:195], v[164:167], v[70:73]
	v_mfma_f32_16x16x32_bf16 v[82:85], v[208:211], v[164:167], v[82:85]
	v_mfma_f32_16x16x32_bf16 v[88:91], v[212:215], v[164:167], v[88:91]
	v_mfma_f32_16x16x32_bf16 v[92:95], v[188:191], v[168:171], v[92:95]
	v_mfma_f32_16x16x32_bf16 v[96:99], v[192:195], v[168:171], v[96:99]
	v_mfma_f32_16x16x32_bf16 v[100:103], v[208:211], v[168:171], v[100:103]
	v_mfma_f32_16x16x32_bf16 v[106:109], v[212:215], v[168:171], v[106:109]
	v_mfma_f32_16x16x32_bf16 v[110:113], v[188:191], v[174:177], v[110:113]
	v_mfma_f32_16x16x32_bf16 v[114:117], v[192:195], v[174:177], v[114:117]
	v_mfma_f32_16x16x32_bf16 v[118:121], v[208:211], v[174:177], v[118:121]
	v_mfma_f32_16x16x32_bf16 v[122:125], v[212:215], v[174:177], v[122:125]
	v_mfma_f32_16x16x32_bf16 v[126:129], v[188:191], v[182:185], v[126:129]
	v_mfma_f32_16x16x32_bf16 v[136:139], v[192:195], v[182:185], v[136:139]
	v_mfma_f32_16x16x32_bf16 v[140:143], v[208:211], v[182:185], v[140:143]
	v_mfma_f32_16x16x32_bf16 v[144:147], v[212:215], v[182:185], v[144:147]
	s_setprio 0
	ds_read_b128 v[148:151], v80 offset:0
	ds_read_b128 v[152:155], v80 offset:2048
	ds_read_b128 v[156:159], v80 offset:4096
	ds_read_b128 v[160:163], v80 offset:6144
	ds_read_b128 v[164:167], v80 offset:16384
	ds_read_b128 v[168:171], v80 offset:18432
	ds_read_b128 v[174:177], v80 offset:20480
	ds_read_b128 v[182:185], v80 offset:22528
	ds_read_b128 v[188:191], v81 offset:49152
	ds_read_b128 v[192:195], v81 offset:51200
	ds_read_b128 v[208:211], v81 offset:53248
	ds_read_b128 v[212:215], v81 offset:55296
	s_waitcnt lgkmcnt(0)
	s_setprio 1
	v_mfma_f32_16x16x32_bf16 v[62:65], v[188:191], v[148:151], v[62:65]
	v_mfma_f32_16x16x32_bf16 v[58:61], v[192:195], v[148:151], v[58:61]
	v_mfma_f32_16x16x32_bf16 v[54:57], v[208:211], v[148:151], v[54:57]
	v_mfma_f32_16x16x32_bf16 v[50:53], v[212:215], v[148:151], v[50:53]
	v_mfma_f32_16x16x32_bf16 v[46:49], v[188:191], v[152:155], v[46:49]
	v_mfma_f32_16x16x32_bf16 v[42:45], v[192:195], v[152:155], v[42:45]
	v_mfma_f32_16x16x32_bf16 v[38:41], v[208:211], v[152:155], v[38:41]
	v_mfma_f32_16x16x32_bf16 v[34:37], v[212:215], v[152:155], v[34:37]
	v_mfma_f32_16x16x32_bf16 v[30:33], v[188:191], v[156:159], v[30:33]
	v_mfma_f32_16x16x32_bf16 v[26:29], v[192:195], v[156:159], v[26:29]
	v_mfma_f32_16x16x32_bf16 v[22:25], v[208:211], v[156:159], v[22:25]
	v_mfma_f32_16x16x32_bf16 v[18:21], v[212:215], v[156:159], v[18:21]
	v_mfma_f32_16x16x32_bf16 v[14:17], v[188:191], v[160:163], v[14:17]
	v_mfma_f32_16x16x32_bf16 v[10:13], v[192:195], v[160:163], v[10:13]
	v_mfma_f32_16x16x32_bf16 v[6:9], v[208:211], v[160:163], v[6:9]
	v_mfma_f32_16x16x32_bf16 v[2:5], v[212:215], v[160:163], v[2:5]
	v_mfma_f32_16x16x32_bf16 v[66:69], v[188:191], v[164:167], v[66:69]
	v_mfma_f32_16x16x32_bf16 v[70:73], v[192:195], v[164:167], v[70:73]
	v_mfma_f32_16x16x32_bf16 v[82:85], v[208:211], v[164:167], v[82:85]
	v_mfma_f32_16x16x32_bf16 v[88:91], v[212:215], v[164:167], v[88:91]
	v_mfma_f32_16x16x32_bf16 v[92:95], v[188:191], v[168:171], v[92:95]
	v_mfma_f32_16x16x32_bf16 v[96:99], v[192:195], v[168:171], v[96:99]
	v_mfma_f32_16x16x32_bf16 v[100:103], v[208:211], v[168:171], v[100:103]
	v_mfma_f32_16x16x32_bf16 v[106:109], v[212:215], v[168:171], v[106:109]
	v_mfma_f32_16x16x32_bf16 v[110:113], v[188:191], v[174:177], v[110:113]
	v_mfma_f32_16x16x32_bf16 v[114:117], v[192:195], v[174:177], v[114:117]
	v_mfma_f32_16x16x32_bf16 v[118:121], v[208:211], v[174:177], v[118:121]
	v_mfma_f32_16x16x32_bf16 v[122:125], v[212:215], v[174:177], v[122:125]
	v_mfma_f32_16x16x32_bf16 v[126:129], v[188:191], v[182:185], v[126:129]
	v_mfma_f32_16x16x32_bf16 v[136:139], v[192:195], v[182:185], v[136:139]
	v_mfma_f32_16x16x32_bf16 v[140:143], v[208:211], v[182:185], v[140:143]
	v_mfma_f32_16x16x32_bf16 v[144:147], v[212:215], v[182:185], v[144:147]
	s_setprio 0
	s_nop 7
	s_nop 7
	s_nop 7
	v_mov_b32_e32 v148, v66
	v_mov_b32_e32 v149, v67
	v_mov_b32_e32 v150, v68
	v_mov_b32_e32 v151, v69
	v_mov_b32_e32 v152, v70
	v_mov_b32_e32 v153, v71
	v_mov_b32_e32 v154, v72
	v_mov_b32_e32 v155, v73
	v_mov_b32_e32 v156, v82
	v_mov_b32_e32 v157, v83
	v_mov_b32_e32 v158, v84
	v_mov_b32_e32 v159, v85
	v_mov_b32_e32 v160, v88
	v_mov_b32_e32 v161, v89
	v_mov_b32_e32 v162, v90
	v_mov_b32_e32 v163, v91
	v_mov_b32_e32 v164, v92
	v_mov_b32_e32 v165, v93
	v_mov_b32_e32 v166, v94
	v_mov_b32_e32 v167, v95
	v_mov_b32_e32 v168, v96
	v_mov_b32_e32 v169, v97
	v_mov_b32_e32 v170, v98
	v_mov_b32_e32 v171, v99
	v_mov_b32_e32 v174, v100
	v_mov_b32_e32 v175, v101
	v_mov_b32_e32 v176, v102
	v_mov_b32_e32 v177, v103
	v_mov_b32_e32 v182, v106
	v_mov_b32_e32 v183, v107
	v_mov_b32_e32 v184, v108
	v_mov_b32_e32 v185, v109
	v_mov_b32_e32 v188, v110
	v_mov_b32_e32 v189, v111
	v_mov_b32_e32 v190, v112
	v_mov_b32_e32 v191, v113
	v_mov_b32_e32 v192, v114
	v_mov_b32_e32 v193, v115
	v_mov_b32_e32 v194, v116
	v_mov_b32_e32 v195, v117
	v_mov_b32_e32 v208, v118
	v_mov_b32_e32 v209, v119
	v_mov_b32_e32 v210, v120
	v_mov_b32_e32 v211, v121
	v_mov_b32_e32 v212, v122
	v_mov_b32_e32 v213, v123
	v_mov_b32_e32 v214, v124
	v_mov_b32_e32 v215, v125
	v_mov_b32_e32 v216, v126
	v_mov_b32_e32 v217, v127
	v_mov_b32_e32 v218, v128
	v_mov_b32_e32 v219, v129
	v_mov_b32_e32 v220, v136
	v_mov_b32_e32 v221, v137
	v_mov_b32_e32 v222, v138
	v_mov_b32_e32 v223, v139
	v_mov_b32_e32 v242, v140
	v_mov_b32_e32 v243, v141
	v_mov_b32_e32 v244, v142
	v_mov_b32_e32 v245, v143
	v_mov_b32_e32 v199, v144
	v_mov_b32_e32 v206, v145
	v_mov_b32_e32 v207, v146
	v_mov_b32_e32 v226, v147
	s_mov_b32 s32, 1
	s_branch .LBB0_222
.Lg2_ret:
	s_cmp_eq_u32 s32, 1
	s_cbranch_scc0 .Lg2_next
	s_mov_b32 s32, 2
	s_mov_b32 s0, s49
	v_mov_b32_e32 v62, v148
	v_mov_b32_e32 v63, v149
	v_mov_b32_e32 v64, v150
	v_mov_b32_e32 v65, v151
	v_mov_b32_e32 v58, v152
	v_mov_b32_e32 v59, v153
	v_mov_b32_e32 v60, v154
	v_mov_b32_e32 v61, v155
	v_mov_b32_e32 v54, v156
	v_mov_b32_e32 v55, v157
	v_mov_b32_e32 v56, v158
	v_mov_b32_e32 v57, v159
	v_mov_b32_e32 v50, v160
	v_mov_b32_e32 v51, v161
	v_mov_b32_e32 v52, v162
	v_mov_b32_e32 v53, v163
	v_mov_b32_e32 v46, v164
	v_mov_b32_e32 v47, v165
	v_mov_b32_e32 v48, v166
	v_mov_b32_e32 v49, v167
	v_mov_b32_e32 v42, v168
	v_mov_b32_e32 v43, v169
	v_mov_b32_e32 v44, v170
	v_mov_b32_e32 v45, v171
	v_mov_b32_e32 v38, v174
	v_mov_b32_e32 v39, v175
	v_mov_b32_e32 v40, v176
	v_mov_b32_e32 v41, v177
	v_mov_b32_e32 v34, v182
	v_mov_b32_e32 v35, v183
	v_mov_b32_e32 v36, v184
	v_mov_b32_e32 v37, v185
	v_mov_b32_e32 v30, v188
	v_mov_b32_e32 v31, v189
	v_mov_b32_e32 v32, v190
	v_mov_b32_e32 v33, v191
	v_mov_b32_e32 v26, v192
	v_mov_b32_e32 v27, v193
	v_mov_b32_e32 v28, v194
	v_mov_b32_e32 v29, v195
	v_mov_b32_e32 v22, v208
	v_mov_b32_e32 v23, v209
	v_mov_b32_e32 v24, v210
	v_mov_b32_e32 v25, v211
	v_mov_b32_e32 v18, v212
	v_mov_b32_e32 v19, v213
	v_mov_b32_e32 v20, v214
	v_mov_b32_e32 v21, v215
	v_mov_b32_e32 v14, v216
	v_mov_b32_e32 v15, v217
	v_mov_b32_e32 v16, v218
	v_mov_b32_e32 v17, v219
	v_mov_b32_e32 v10, v220
	v_mov_b32_e32 v11, v221
	v_mov_b32_e32 v12, v222
	v_mov_b32_e32 v13, v223
	v_mov_b32_e32 v6, v242
	v_mov_b32_e32 v7, v243
	v_mov_b32_e32 v8, v244
	v_mov_b32_e32 v9, v245
	v_mov_b32_e32 v2, v199
	v_mov_b32_e32 v3, v206
	v_mov_b32_e32 v4, v207
	v_mov_b32_e32 v5, v226
	s_branch .LBB0_222
.Lg2_next:
	s_add_i32 s48, s48, 1
	s_branch .Lg2_tile
.Lg2_done:
	s_mov_b32 s32, 0
	s_branch .LBB0_476
.LBB0_211:
	s_cmp_lg_u32 s32, 0
	s_cbranch_scc1 .Lg2_ret
	s_cmp_lg_u32 s36, s26
	s_mov_b32 s1, s36
	s_cbranch_scc0 .LBB0_476
